# attention hot path: rescale decision after MFMA 15
# baseline (speedup 1.0000x reference)
.Latt_prio_skip:
	v_xor_b32_e32 v84, 0x80000000, v239
	v_mov_b32_e32 v85, v84
	v_mov_b32_e32 v86, v84
	v_mov_b32_e32 v87, v84
	v_mov_b32_e32 v88, v84
	v_mov_b32_e32 v89, v84
	v_mov_b32_e32 v90, v84
	v_mov_b32_e32 v91, v84
	v_mov_b32_e32 v92, v84
	v_mov_b32_e32 v93, v84
	v_mov_b32_e32 v94, v84
	v_mov_b32_e32 v95, v84
	v_mov_b32_e32 v96, v84
	v_mov_b32_e32 v97, v84
	v_mov_b32_e32 v98, v84
	v_mov_b32_e32 v99, v84
	s_waitcnt lgkmcnt(5)
	s_nop 0
	v_mfma_f32_32x32x16_bf16 v[36:51], v[100:103], v[132:135], v[84:99]
	ds_read_b128 v[100:103], v124 offset:6656
	s_waitcnt lgkmcnt(5)
	v_mfma_f32_32x32x16_bf16 v[36:51], v[104:107], v[136:139], v[36:51]
	ds_read_b128 v[104:107], v124 offset:6688
	s_waitcnt lgkmcnt(5)
	v_mfma_f32_32x32x16_bf16 v[36:51], v[108:111], v[140:143], v[36:51]
	ds_read_b128 v[108:111], v124 offset:6720
	s_waitcnt lgkmcnt(5)
	v_mfma_f32_32x32x16_bf16 v[36:51], v[112:115], v[144:147], v[36:51]
	ds_read_b128 v[112:115], v124 offset:6752
	s_waitcnt lgkmcnt(5)
	v_mfma_f32_32x32x16_bf16 v[36:51], v[116:119], v[148:151], v[36:51]
	ds_read_b128 v[116:119], v124 offset:6784
	s_waitcnt lgkmcnt(5)
	v_mfma_f32_32x32x16_bf16 v[36:51], v[120:123], v[152:155], v[36:51]
	ds_read_b128 v[120:123], v124 offset:6816
	s_waitcnt lgkmcnt(5)
	v_mfma_f32_32x32x16_bf16 v[52:67], v[100:103], v[132:135], v[84:99]
	ds_read_b128 v[100:103], v124 offset:13312
	s_waitcnt lgkmcnt(5)
	v_mfma_f32_32x32x16_bf16 v[52:67], v[104:107], v[136:139], v[52:67]
	ds_read_b128 v[104:107], v124 offset:13344
	s_waitcnt lgkmcnt(5)
	v_mfma_f32_32x32x16_bf16 v[52:67], v[108:111], v[140:143], v[52:67]
	ds_read_b128 v[108:111], v124 offset:13376
	s_waitcnt lgkmcnt(5)
	v_mfma_f32_32x32x16_bf16 v[52:67], v[112:115], v[144:147], v[52:67]
	ds_read_b128 v[112:115], v124 offset:13408
	s_waitcnt lgkmcnt(5)
	v_mfma_f32_32x32x16_bf16 v[52:67], v[116:119], v[148:151], v[52:67]
	ds_read_b128 v[116:119], v124 offset:13440
	s_waitcnt lgkmcnt(5)
	v_mfma_f32_32x32x16_bf16 v[52:67], v[120:123], v[152:155], v[52:67]
	ds_read_b128 v[120:123], v124 offset:13472
	s_waitcnt lgkmcnt(5)
	v_mfma_f32_32x32x16_bf16 v[68:83], v[100:103], v[132:135], v[84:99]
	ds_read_b128 v[100:103], v124 offset:19968
	v_max3_f32 v125, v36, v37, v38
	v_max3_f32 v125, v125, v39, v40
	v_max3_f32 v125, v125, v41, v42
	v_max3_f32 v125, v125, v43, v44
	v_max3_f32 v125, v125, v45, v46
	v_max3_f32 v125, v125, v47, v48
	v_max3_f32 v125, v125, v49, v50
	s_waitcnt lgkmcnt(5)
	v_mfma_f32_32x32x16_bf16 v[68:83], v[104:107], v[136:139], v[68:83]
	ds_read_b128 v[104:107], v124 offset:20000
	v_max3_f32 v129, v51, v52, v53
	v_max3_f32 v129, v129, v54, v55
	v_max3_f32 v129, v129, v56, v57
	v_max3_f32 v129, v129, v58, v59
	v_max3_f32 v129, v129, v60, v61
	v_max3_f32 v129, v129, v62, v63
	v_max3_f32 v129, v129, v64, v65
	s_waitcnt lgkmcnt(5)
	v_mfma_f32_32x32x16_bf16 v[68:83], v[108:111], v[140:143], v[68:83]
	ds_read_b128 v[108:111], v124 offset:20032
	v_max3_f32 v129, v129, v66, v67
	v_max_f32_e32 v125, v125, v129
	v_mov_b32_e32 v126, v125
	s_nop 1
	v_permlane32_swap_b32_e32 v125, v126
	v_max_f32_e32 v125, v125, v126
	s_cmp_eq_u32 s86, 0
	s_cbranch_scc1 .Latt_slow0
	v_cmp_lt_f32_e32 vcc, s95, v125
	s_cbranch_vccnz .Latt_slow0
	s_waitcnt lgkmcnt(5)
	v_mfma_f32_32x32x16_bf16 v[68:83], v[112:115], v[144:147], v[68:83]
	ds_read_b128 v[112:115], v124 offset:20064
	v_exp_f32_e32 v36, v36
	v_exp_f32_e32 v37, v37
	v_exp_f32_e32 v38, v38
	v_exp_f32_e32 v39, v39
	v_exp_f32_e32 v40, v40
	v_exp_f32_e32 v41, v41
	v_exp_f32_e32 v42, v42
	v_exp_f32_e32 v43, v43
	v_add_f32_e32 v127, v36, v37
	s_waitcnt lgkmcnt(5)
	v_mfma_f32_32x32x16_bf16 v[68:83], v[116:119], v[148:151], v[68:83]
	ds_read_b128 v[116:119], v124 offset:20096
	v_add_f32_e32 v127, v38, v127
	v_add_f32_e32 v127, v39, v127
	v_add_f32_e32 v127, v40, v127
	v_add_f32_e32 v127, v41, v127
	v_add_f32_e32 v127, v42, v127
	v_add_f32_e32 v127, v43, v127
	v_cvt_pk_bf16_f32 v36, v36, v37
	v_cvt_pk_bf16_f32 v37, v38, v39
	v_cvt_pk_bf16_f32 v38, v40, v41
	s_waitcnt lgkmcnt(5)
	v_mfma_f32_32x32x16_bf16 v[68:83], v[120:123], v[152:155], v[68:83]
	ds_read_b128 v[120:123], v124 offset:20128
	v_cvt_pk_bf16_f32 v39, v42, v43
	v_exp_f32_e32 v44, v44
	v_exp_f32_e32 v45, v45
	v_exp_f32_e32 v46, v46
	v_exp_f32_e32 v47, v47
	v_exp_f32_e32 v48, v48
	v_exp_f32_e32 v49, v49
	v_exp_f32_e32 v50, v50
	v_exp_f32_e32 v51, v51
	s_waitcnt lgkmcnt(5)
	v_mfma_f32_32x32x16_bf16 v[84:99], v[100:103], v[132:135], v[84:99]
	ds_read_b128 v[100:103], v185 offset:26624
	v_add_f32_e32 v127, v44, v127
	v_add_f32_e32 v127, v45, v127
	v_add_f32_e32 v127, v46, v127
	v_add_f32_e32 v127, v47, v127
	v_add_f32_e32 v127, v48, v127
	v_add_f32_e32 v127, v49, v127
	v_add_f32_e32 v127, v50, v127
	v_add_f32_e32 v127, v51, v127
	v_cvt_pk_bf16_f32 v40, v44, v45
	s_waitcnt lgkmcnt(5)
	v_mfma_f32_32x32x16_bf16 v[84:99], v[104:107], v[136:139], v[84:99]
	ds_read_b128 v[104:107], v185 offset:35328
	v_cvt_pk_bf16_f32 v41, v46, v47
	v_cvt_pk_bf16_f32 v42, v48, v49
	v_cvt_pk_bf16_f32 v43, v50, v51
	v_exp_f32_e32 v52, v52
	v_exp_f32_e32 v53, v53
	v_exp_f32_e32 v54, v54
	v_exp_f32_e32 v55, v55
	v_exp_f32_e32 v56, v56
	v_exp_f32_e32 v57, v57
	s_waitcnt lgkmcnt(5)
	v_mfma_f32_32x32x16_bf16 v[84:99], v[108:111], v[140:143], v[84:99]
	ds_read_b128 v[108:111], v185 offset:26656
	v_exp_f32_e32 v58, v58
	v_exp_f32_e32 v59, v59
	v_add_f32_e32 v128, v52, v53
	v_add_f32_e32 v128, v54, v128
	v_add_f32_e32 v128, v55, v128
	v_add_f32_e32 v128, v56, v128
	v_add_f32_e32 v128, v57, v128
	v_add_f32_e32 v128, v58, v128
	v_add_f32_e32 v128, v59, v128
	s_waitcnt lgkmcnt(5)
	v_mfma_f32_32x32x16_bf16 v[84:99], v[112:115], v[144:147], v[84:99]
	ds_read_b128 v[112:115], v185 offset:35360
	v_cvt_pk_bf16_f32 v52, v52, v53
	v_cvt_pk_bf16_f32 v53, v54, v55
	v_cvt_pk_bf16_f32 v54, v56, v57
	v_cvt_pk_bf16_f32 v55, v58, v59
	v_exp_f32_e32 v60, v60
	v_exp_f32_e32 v61, v61
	v_exp_f32_e32 v62, v62
	v_exp_f32_e32 v63, v63
	v_exp_f32_e32 v64, v64
	s_waitcnt lgkmcnt(5)
	v_mfma_f32_32x32x16_bf16 v[84:99], v[116:119], v[148:151], v[84:99]
	ds_read_b128 v[116:119], v185 offset:26688
	v_exp_f32_e32 v65, v65
	v_exp_f32_e32 v66, v66
	v_exp_f32_e32 v67, v67
	v_add_f32_e32 v128, v60, v128
	v_add_f32_e32 v128, v61, v128
	v_add_f32_e32 v128, v62, v128
	v_add_f32_e32 v128, v63, v128
	v_add_f32_e32 v128, v64, v128
	v_add_f32_e32 v128, v65, v128
	s_waitcnt lgkmcnt(5)
	v_mfma_f32_32x32x16_bf16 v[84:99], v[120:123], v[152:155], v[84:99]
	ds_read_b128 v[120:123], v185 offset:35392
	v_add_f32_e32 v128, v66, v128
	v_add_f32_e32 v128, v67, v128
	v_cvt_pk_bf16_f32 v56, v60, v61
	v_cvt_pk_bf16_f32 v57, v62, v63
	v_cvt_pk_bf16_f32 v58, v64, v65
	v_cvt_pk_bf16_f32 v59, v66, v67
	v_add_f32_e32 v127, v127, v128
	v_add_f32_e32 v238, v238, v127
	s_waitcnt lgkmcnt(5)
	v_mfma_f32_32x32x16_bf16 v[4:19], v[100:103], v[36:39], v[4:19]
	ds_read_b128 v[100:103], v185 offset:26720
	v_max3_f32 v125, v68, v69, v70
	v_max3_f32 v125, v125, v71, v72
	v_max3_f32 v125, v125, v73, v74
	v_max3_f32 v125, v125, v75, v76
	v_max3_f32 v125, v125, v77, v78
	v_max3_f32 v125, v125, v79, v80
	v_max3_f32 v125, v125, v81, v82
	s_waitcnt lgkmcnt(5)
	v_mfma_f32_32x32x16_bf16 v[20:35], v[104:107], v[36:39], v[20:35]
	ds_read_b128 v[104:107], v185 offset:35424
	v_max3_f32 v129, v83, v84, v85
	v_max3_f32 v129, v129, v86, v87
	v_max3_f32 v129, v129, v88, v89
	v_max3_f32 v129, v129, v90, v91
	v_max3_f32 v129, v129, v92, v93
	v_max3_f32 v129, v129, v94, v95
	v_max3_f32 v129, v129, v96, v97
	s_waitcnt lgkmcnt(5)
	v_mfma_f32_32x32x16_bf16 v[4:19], v[108:111], v[40:43], v[4:19]
	ds_read_b128 v[108:111], v185 offset:26752
	v_max3_f32 v129, v129, v98, v99
	v_max_f32_e32 v125, v125, v129
	v_mov_b32_e32 v126, v125
	s_nop 1
	v_permlane32_swap_b32_e32 v125, v126
	v_max_f32_e32 v125, v125, v126
	v_cmp_lt_f32_e32 vcc, s95, v125
	s_cbranch_vccnz .Latt_slow1
	s_waitcnt lgkmcnt(5)
	v_mfma_f32_32x32x16_bf16 v[20:35], v[112:115], v[40:43], v[20:35]
	ds_read_b128 v[112:115], v185 offset:35456
	v_exp_f32_e32 v68, v68
	v_exp_f32_e32 v69, v69
	v_exp_f32_e32 v70, v70
	v_exp_f32_e32 v71, v71
	v_exp_f32_e32 v72, v72
	v_exp_f32_e32 v73, v73
	v_exp_f32_e32 v74, v74
	v_exp_f32_e32 v75, v75
	v_add_f32_e32 v127, v68, v69
	v_add_f32_e32 v127, v70, v127
	v_add_f32_e32 v127, v71, v127
	v_add_f32_e32 v127, v72, v127
	v_add_f32_e32 v127, v73, v127
	v_add_f32_e32 v127, v74, v127
	v_add_f32_e32 v127, v75, v127
	v_cvt_pk_bf16_f32 v68, v68, v69
	s_waitcnt lgkmcnt(5)
	v_mfma_f32_32x32x16_bf16 v[4:19], v[116:119], v[52:55], v[4:19]
	ds_read_b128 v[116:119], v185 offset:26784
	v_cvt_pk_bf16_f32 v69, v70, v71
	v_cvt_pk_bf16_f32 v70, v72, v73
	v_cvt_pk_bf16_f32 v71, v74, v75
	v_exp_f32_e32 v76, v76
	v_exp_f32_e32 v77, v77
	v_exp_f32_e32 v78, v78
	v_exp_f32_e32 v79, v79
	v_exp_f32_e32 v80, v80
	v_exp_f32_e32 v81, v81
	v_exp_f32_e32 v82, v82
	v_exp_f32_e32 v83, v83
	v_add_f32_e32 v127, v76, v127
	v_add_f32_e32 v127, v77, v127
	v_add_f32_e32 v127, v78, v127
	v_add_f32_e32 v127, v79, v127
	v_add_f32_e32 v127, v80, v127
	s_waitcnt lgkmcnt(5)
	v_mfma_f32_32x32x16_bf16 v[20:35], v[120:123], v[52:55], v[20:35]
	ds_read_b128 v[120:123], v185 offset:35488
	v_add_f32_e32 v127, v81, v127
	v_add_f32_e32 v127, v82, v127
	v_add_f32_e32 v127, v83, v127
	v_cvt_pk_bf16_f32 v72, v76, v77
	v_cvt_pk_bf16_f32 v73, v78, v79
	v_cvt_pk_bf16_f32 v74, v80, v81
	v_cvt_pk_bf16_f32 v75, v82, v83
	v_exp_f32_e32 v84, v84
	v_exp_f32_e32 v85, v85
	v_exp_f32_e32 v86, v86
	v_exp_f32_e32 v87, v87
	v_exp_f32_e32 v88, v88
	v_exp_f32_e32 v89, v89
	v_exp_f32_e32 v90, v90
	v_exp_f32_e32 v91, v91
	v_add_f32_e32 v128, v84, v85
	s_waitcnt lgkmcnt(5)
	v_mfma_f32_32x32x16_bf16 v[4:19], v[100:103], v[56:59], v[4:19]
	ds_read_b128 v[100:103], v185 offset:26816
	v_add_f32_e32 v128, v86, v128
	v_add_f32_e32 v128, v87, v128
	v_add_f32_e32 v128, v88, v128
	v_add_f32_e32 v128, v89, v128
	v_add_f32_e32 v128, v90, v128
	v_add_f32_e32 v128, v91, v128
	v_cvt_pk_bf16_f32 v84, v84, v85
	v_cvt_pk_bf16_f32 v85, v86, v87
	v_cvt_pk_bf16_f32 v86, v88, v89
	v_cvt_pk_bf16_f32 v87, v90, v91
	v_exp_f32_e32 v92, v92
	v_exp_f32_e32 v93, v93
	v_exp_f32_e32 v94, v94
	v_exp_f32_e32 v95, v95
	v_exp_f32_e32 v96, v96
	v_exp_f32_e32 v97, v97
	s_waitcnt lgkmcnt(5)
	v_mfma_f32_32x32x16_bf16 v[20:35], v[104:107], v[56:59], v[20:35]
	ds_read_b128 v[104:107], v185 offset:35520
	v_exp_f32_e32 v98, v98
	v_exp_f32_e32 v99, v99
	v_add_f32_e32 v128, v92, v128
	v_add_f32_e32 v128, v93, v128
	v_add_f32_e32 v128, v94, v128
	v_add_f32_e32 v128, v95, v128
	v_add_f32_e32 v128, v96, v128
	v_add_f32_e32 v128, v97, v128
	v_add_f32_e32 v128, v98, v128
	v_add_f32_e32 v128, v99, v128
	v_cvt_pk_bf16_f32 v88, v92, v93
	v_cvt_pk_bf16_f32 v89, v94, v95
	v_cvt_pk_bf16_f32 v90, v96, v97
	v_cvt_pk_bf16_f32 v91, v98, v99
	v_add_f32_e32 v127, v127, v128
	v_add_f32_e32 v238, v238, v127
	s_waitcnt lgkmcnt(5)
	v_mfma_f32_32x32x16_bf16 v[4:19], v[108:111], v[68:71], v[4:19]
	ds_read_b128 v[108:111], v185 offset:26848
	s_waitcnt lgkmcnt(5)
	v_mfma_f32_32x32x16_bf16 v[20:35], v[112:115], v[68:71], v[20:35]
	ds_read_b128 v[112:115], v185 offset:35552
	s_waitcnt lgkmcnt(5)
	v_mfma_f32_32x32x16_bf16 v[4:19], v[116:119], v[72:75], v[4:19]
	s_waitcnt lgkmcnt(4)
	v_mfma_f32_32x32x16_bf16 v[20:35], v[120:123], v[72:75], v[20:35]
	s_waitcnt lgkmcnt(3)
	v_mfma_f32_32x32x16_bf16 v[4:19], v[100:103], v[84:87], v[4:19]
	s_waitcnt lgkmcnt(2)
	v_mfma_f32_32x32x16_bf16 v[20:35], v[104:107], v[84:87], v[20:35]
	s_waitcnt lgkmcnt(1)
	v_mfma_f32_32x32x16_bf16 v[4:19], v[108:111], v[88:91], v[4:19]
	s_waitcnt lgkmcnt(0)
	v_mfma_f32_32x32x16_bf16 v[20:35], v[112:115], v[88:91], v[20:35]
	s_setprio 0
	s_branch .LBB0_631
.Latt_slow0:
	s_waitcnt lgkmcnt(5)
	v_mfma_f32_32x32x16_bf16 v[68:83], v[112:115], v[144:147], v[68:83]
	ds_read_b128 v[112:115], v124 offset:20064
	s_waitcnt lgkmcnt(5)
	v_mfma_f32_32x32x16_bf16 v[68:83], v[116:119], v[148:151], v[68:83]
	ds_read_b128 v[116:119], v124 offset:20096
	s_waitcnt lgkmcnt(5)
	v_mfma_f32_32x32x16_bf16 v[68:83], v[120:123], v[152:155], v[68:83]
	ds_read_b128 v[120:123], v124 offset:20128
	s_waitcnt lgkmcnt(5)
	v_mfma_f32_32x32x16_bf16 v[84:99], v[100:103], v[132:135], v[84:99]
	ds_read_b128 v[100:103], v185 offset:26624
	s_waitcnt lgkmcnt(5)
	v_mfma_f32_32x32x16_bf16 v[84:99], v[104:107], v[136:139], v[84:99]
	ds_read_b128 v[104:107], v185 offset:35328
	s_waitcnt lgkmcnt(5)
	v_mfma_f32_32x32x16_bf16 v[84:99], v[108:111], v[140:143], v[84:99]
	ds_read_b128 v[108:111], v185 offset:26656
	s_waitcnt lgkmcnt(5)
	v_mfma_f32_32x32x16_bf16 v[84:99], v[112:115], v[144:147], v[84:99]
	ds_read_b128 v[112:115], v185 offset:35360
	s_waitcnt lgkmcnt(5)
	v_mfma_f32_32x32x16_bf16 v[84:99], v[116:119], v[148:151], v[84:99]
	ds_read_b128 v[116:119], v185 offset:26688
	s_waitcnt lgkmcnt(5)
	v_mfma_f32_32x32x16_bf16 v[84:99], v[120:123], v[152:155], v[84:99]
	ds_read_b128 v[120:123], v185 offset:35392
	v_max_f32_e32 v130, 0, v125
	s_cmp_eq_u32 s86, 0
	s_cselect_b64 s[78:79], -1, 0
	v_cndmask_b32_e64 v130, v130, v125, s[78:79]
	v_exp_f32_e64 v131, -v130
	v_mov_b32_e32 v187, v130
	v_add_f32_e32 v239, v239, v130
	v_cndmask_b32_e64 v131, v131, 0, s[78:79]
	v_sub_f32_e32 v36, v36, v187
	v_sub_f32_e32 v37, v37, v187
	v_sub_f32_e32 v38, v38, v187
	v_sub_f32_e32 v39, v39, v187
	v_sub_f32_e32 v40, v40, v187
	v_sub_f32_e32 v41, v41, v187
	v_sub_f32_e32 v42, v42, v187
	v_sub_f32_e32 v43, v43, v187
	v_sub_f32_e32 v44, v44, v187
	v_sub_f32_e32 v45, v45, v187
	v_sub_f32_e32 v46, v46, v187
	v_sub_f32_e32 v47, v47, v187
	v_sub_f32_e32 v48, v48, v187
	v_sub_f32_e32 v49, v49, v187
	v_sub_f32_e32 v50, v50, v187
	v_sub_f32_e32 v51, v51, v187
	v_sub_f32_e32 v52, v52, v187
	v_sub_f32_e32 v53, v53, v187
	v_sub_f32_e32 v54, v54, v187
	v_sub_f32_e32 v55, v55, v187
	v_sub_f32_e32 v56, v56, v187
	v_sub_f32_e32 v57, v57, v187
	v_sub_f32_e32 v58, v58, v187
	v_sub_f32_e32 v59, v59, v187
	v_sub_f32_e32 v60, v60, v187
	v_sub_f32_e32 v61, v61, v187
	v_sub_f32_e32 v62, v62, v187
	v_sub_f32_e32 v63, v63, v187
	v_sub_f32_e32 v64, v64, v187
	v_sub_f32_e32 v65, v65, v187
	v_sub_f32_e32 v66, v66, v187
	v_sub_f32_e32 v67, v67, v187
	v_exp_f32_e32 v36, v36
	v_exp_f32_e32 v37, v37
	v_exp_f32_e32 v38, v38
	v_exp_f32_e32 v39, v39
	v_exp_f32_e32 v40, v40
	v_exp_f32_e32 v41, v41
	v_exp_f32_e32 v42, v42
	v_exp_f32_e32 v43, v43
	v_exp_f32_e32 v44, v44
	v_exp_f32_e32 v45, v45
	v_exp_f32_e32 v46, v46
	v_exp_f32_e32 v47, v47
	v_exp_f32_e32 v48, v48
	v_exp_f32_e32 v49, v49
	v_exp_f32_e32 v50, v50
	v_exp_f32_e32 v51, v51
	v_exp_f32_e32 v52, v52
	v_exp_f32_e32 v53, v53
	v_exp_f32_e32 v54, v54
	v_exp_f32_e32 v55, v55
	v_exp_f32_e32 v56, v56
	v_exp_f32_e32 v57, v57
	v_exp_f32_e32 v58, v58
	v_exp_f32_e32 v59, v59
	v_exp_f32_e32 v60, v60
	v_exp_f32_e32 v61, v61
	v_exp_f32_e32 v62, v62
	v_exp_f32_e32 v63, v63
	v_exp_f32_e32 v64, v64
	v_exp_f32_e32 v65, v65
	v_exp_f32_e32 v66, v66
	v_exp_f32_e32 v67, v67
	v_add_f32_e32 v127, v36, v37
	v_add_f32_e32 v127, v38, v127
	v_add_f32_e32 v127, v39, v127
	v_add_f32_e32 v127, v40, v127
	v_add_f32_e32 v127, v41, v127
	v_add_f32_e32 v127, v42, v127
	v_add_f32_e32 v127, v43, v127
	v_add_f32_e32 v127, v44, v127
	v_add_f32_e32 v127, v45, v127
	v_add_f32_e32 v127, v46, v127
	v_add_f32_e32 v127, v47, v127
	v_add_f32_e32 v127, v48, v127
	v_add_f32_e32 v127, v49, v127
	v_add_f32_e32 v127, v50, v127
	v_add_f32_e32 v127, v51, v127
	v_add_f32_e32 v127, v52, v127
	v_add_f32_e32 v127, v53, v127
	v_add_f32_e32 v127, v54, v127
	v_add_f32_e32 v127, v55, v127
	v_add_f32_e32 v127, v56, v127
	v_add_f32_e32 v127, v57, v127
	v_add_f32_e32 v127, v58, v127
	v_add_f32_e32 v127, v59, v127
	v_add_f32_e32 v127, v60, v127
	v_add_f32_e32 v127, v61, v127
	v_add_f32_e32 v127, v62, v127
	v_add_f32_e32 v127, v63, v127
	v_add_f32_e32 v127, v64, v127
	v_add_f32_e32 v127, v65, v127
	v_add_f32_e32 v127, v66, v127
	v_add_f32_e32 v127, v67, v127
	v_mul_f32_e32 v238, v238, v131
	v_add_f32_e32 v238, v238, v127
	v_mul_f32_e32 v4, v4, v131
	v_mul_f32_e32 v5, v5, v131
	v_mul_f32_e32 v6, v6, v131
	v_mul_f32_e32 v7, v7, v131
	v_mul_f32_e32 v8, v8, v131
	v_mul_f32_e32 v9, v9, v131
	v_mul_f32_e32 v10, v10, v131
	v_mul_f32_e32 v11, v11, v131
	v_mul_f32_e32 v12, v12, v131
	v_mul_f32_e32 v13, v13, v131
	v_mul_f32_e32 v14, v14, v131
	v_mul_f32_e32 v15, v15, v131
	v_mul_f32_e32 v16, v16, v131
	v_mul_f32_e32 v17, v17, v131
	v_mul_f32_e32 v18, v18, v131
	v_mul_f32_e32 v19, v19, v131
	v_mul_f32_e32 v20, v20, v131
	v_mul_f32_e32 v21, v21, v131
	v_mul_f32_e32 v22, v22, v131
	v_mul_f32_e32 v23, v23, v131
	v_mul_f32_e32 v24, v24, v131
	v_mul_f32_e32 v25, v25, v131
	v_mul_f32_e32 v26, v26, v131
	v_mul_f32_e32 v27, v27, v131
	v_mul_f32_e32 v28, v28, v131
	v_mul_f32_e32 v29, v29, v131
	v_mul_f32_e32 v30, v30, v131
	v_mul_f32_e32 v31, v31, v131
	v_mul_f32_e32 v32, v32, v131
	v_mul_f32_e32 v33, v33, v131
	v_mul_f32_e32 v34, v34, v131
	v_mul_f32_e32 v35, v35, v131
	v_mov_b32_e32 v242, v130
	v_cvt_pk_bf16_f32 v36, v36, v37
	v_cvt_pk_bf16_f32 v37, v38, v39
	v_cvt_pk_bf16_f32 v38, v40, v41
	v_cvt_pk_bf16_f32 v39, v42, v43
	v_cvt_pk_bf16_f32 v40, v44, v45
	v_cvt_pk_bf16_f32 v41, v46, v47
	v_cvt_pk_bf16_f32 v42, v48, v49
	v_cvt_pk_bf16_f32 v43, v50, v51
	v_cvt_pk_bf16_f32 v52, v52, v53
	v_cvt_pk_bf16_f32 v53, v54, v55
	v_cvt_pk_bf16_f32 v54, v56, v57
	v_cvt_pk_bf16_f32 v55, v58, v59
	v_cvt_pk_bf16_f32 v56, v60, v61
	v_cvt_pk_bf16_f32 v57, v62, v63
	v_cvt_pk_bf16_f32 v58, v64, v65
	v_cvt_pk_bf16_f32 v59, v66, v67
	s_waitcnt lgkmcnt(5)
	v_mfma_f32_32x32x16_bf16 v[4:19], v[100:103], v[36:39], v[4:19]
	ds_read_b128 v[100:103], v185 offset:26720
	s_waitcnt lgkmcnt(5)
	v_mfma_f32_32x32x16_bf16 v[20:35], v[104:107], v[36:39], v[20:35]
	ds_read_b128 v[104:107], v185 offset:35424
	s_waitcnt lgkmcnt(5)
	v_mfma_f32_32x32x16_bf16 v[4:19], v[108:111], v[40:43], v[4:19]
	ds_read_b128 v[108:111], v185 offset:26752
	s_branch .Latt_slowb
